# plus: SSD per-row decay weights hoisted out of the divergent staging blocks; Proj epilogue row-stat loads batched
# speedup vs baseline: 1.0127x; 1.0127x over previous
; __device__ __forceinline__ unsigned pk2(float lo, float hi) { return pg8::cvt_pk_bf16(lo, hi); }
; __device__ __forceinline__ float row_rs4(const float* ssq, size_t row, int fq) {
;     const f32x4 a = *(const f32x4*)(ssq + row * 16 + 4 * fq);
;     float s = (a[0] + a[1]) + (a[2] + a[3]);
;     s += __shfl_xor(s, 16); s += __shfl_xor(s, 32);
;     return rsqrtf(s * (1.0f / DM) + EPSN);
; }
;     __device__ __forceinline__ void operator()(const pg8::f32x4 (&acc)[2][2][4][2], const pg8::Unit& u, int wr, int wc, int fr, int fq) const {
;     ...
; #pragma unroll
;         for (int ai = 0; ai < 2; ++ai)
; #pragma unroll
;             for (int m = 0; m < 4; ++m) {
;                 const size_t row = (size_t)(row0 + ai * 128 + m * 16);
;                 const float rs = row_rs4(ssq, row + row_off, fq);
; #pragma unroll
;                 for (int bj = 0; bj < 2; ++bj) {
;                     const pg8::f32x4 v0 = acc[ai][bj][m][0] * rs, v1 = acc[ai][bj][m][1] * rs;
;                     u32x4 w; w.x = pk2(v0[0], v0[1]); w.y = pk2(v0[2], v0[3]); w.z = pk2(v1[0], v1[1]); w.w = pk2(v1[2], v1[3]);
;                     *(u32x4*)(P + row * PLD + col0 + bj * 128) = w;
;                 }
;                 asm volatile("" ::: "memory");
;             }
.LBB0_181:
	v_readlane_b32 s16, v253, 22
	v_readlane_b32 s17, v253, 23
	v_and_b32_e32 v151, 64, v175
	v_xor_b32_e32 v128, 16, v175
	v_add_u32_e32 v151, 64, v151
	v_cmp_lt_i32_e32 vcc, v128, v151
	v_xor_b32_e32 v153, 32, v175
	s_mov_b32 s11, 0x800000
	v_cndmask_b32_e32 v128, v175, v128, vcc
	v_cmp_lt_i32_e32 vcc, v153, v151
	v_lshlrev_b32_e32 v128, 2, v128
	v_readlane_b32 s0, v253, 38
	v_cndmask_b32_e32 v151, v175, v153, vcc
	v_lshlrev_b32_e32 v199, 2, v151
	v_or_b32_e32 v176, s9, v196
	v_readlane_b32 s1, v253, 39
	v_ashrrev_i32_e32 v177, 31, v176
	v_lshlrev_b64 v[168:169], 1, v[176:177]
	v_ashrrev_i32_e32 v165, 31, v164
	v_lshl_add_u64 v[232:233], v[164:165], 0, s[16:17]
	v_lshlrev_b64 v[232:233], 6, v[232:233]
	v_lshl_add_u64 v[232:233], v[140:141], 0, v[232:233]
	global_load_dwordx4 v[200:203], v[232:233], off
	v_ashrrev_i32_e32 v163, 31, v162
	v_lshl_add_u64 v[232:233], v[162:163], 0, s[16:17]
	v_lshlrev_b64 v[232:233], 6, v[232:233]
	v_lshl_add_u64 v[232:233], v[140:141], 0, v[232:233]
	global_load_dwordx4 v[204:207], v[232:233], off
	v_ashrrev_i32_e32 v161, 31, v160
	v_lshl_add_u64 v[232:233], v[160:161], 0, s[16:17]
	v_lshlrev_b64 v[232:233], 6, v[232:233]
	v_lshl_add_u64 v[232:233], v[140:141], 0, v[232:233]
	global_load_dwordx4 v[208:211], v[232:233], off
	v_ashrrev_i32_e32 v159, 31, v158
	v_lshl_add_u64 v[232:233], v[158:159], 0, s[16:17]
	v_lshlrev_b64 v[232:233], 6, v[232:233]
	v_lshl_add_u64 v[232:233], v[140:141], 0, v[232:233]
	global_load_dwordx4 v[212:215], v[232:233], off
	v_ashrrev_i32_e32 v157, 31, v156
	v_lshl_add_u64 v[232:233], v[156:157], 0, s[16:17]
	v_lshlrev_b64 v[232:233], 6, v[232:233]
	v_lshl_add_u64 v[232:233], v[140:141], 0, v[232:233]
	global_load_dwordx4 v[216:219], v[232:233], off
	v_ashrrev_i32_e32 v155, 31, v154
	v_lshl_add_u64 v[232:233], v[154:155], 0, s[16:17]
	v_lshlrev_b64 v[232:233], 6, v[232:233]
	v_lshl_add_u64 v[232:233], v[140:141], 0, v[232:233]
	global_load_dwordx4 v[220:223], v[232:233], off
	v_ashrrev_i32_e32 v153, 31, v152
	v_lshl_add_u64 v[232:233], v[152:153], 0, s[16:17]
	v_lshlrev_b64 v[232:233], 6, v[232:233]
	v_lshl_add_u64 v[232:233], v[140:141], 0, v[232:233]
	global_load_dwordx4 v[224:227], v[232:233], off
	v_ashrrev_i32_e32 v151, 31, v150
	v_lshl_add_u64 v[232:233], v[150:151], 0, s[16:17]
	v_lshlrev_b64 v[232:233], 6, v[232:233]
	v_lshl_add_u64 v[232:233], v[140:141], 0, v[232:233]
	global_load_dwordx4 v[228:231], v[232:233], off
	v_mov_b64_e32 v[166:167], s[0:1]
	s_waitcnt vmcnt(0)
	v_add_f32_e32 v234, v201, v200
	v_add_f32_e32 v242, v202, v203
	v_add_f32_e32 v234, v234, v242
	v_add_f32_e32 v235, v205, v204
	v_add_f32_e32 v243, v206, v207
	v_add_f32_e32 v235, v235, v243
	v_add_f32_e32 v236, v209, v208
	v_add_f32_e32 v244, v210, v211
	v_add_f32_e32 v236, v236, v244
	v_add_f32_e32 v237, v213, v212
	v_add_f32_e32 v245, v214, v215
	v_add_f32_e32 v237, v237, v245
	v_add_f32_e32 v238, v217, v216
	v_add_f32_e32 v246, v218, v219
	v_add_f32_e32 v238, v238, v246
	v_add_f32_e32 v239, v221, v220
	v_add_f32_e32 v247, v222, v223
	v_add_f32_e32 v239, v239, v247
	v_add_f32_e32 v240, v225, v224
	v_add_f32_e32 v248, v226, v227
	v_add_f32_e32 v240, v240, v248
	v_add_f32_e32 v241, v229, v228
	v_add_f32_e32 v249, v230, v231
	v_add_f32_e32 v241, v241, v249
	ds_bpermute_b32 v242, v128, v234
	ds_bpermute_b32 v243, v128, v235
	ds_bpermute_b32 v244, v128, v236
	ds_bpermute_b32 v245, v128, v237
	ds_bpermute_b32 v246, v128, v238
	ds_bpermute_b32 v247, v128, v239
	ds_bpermute_b32 v248, v128, v240
	ds_bpermute_b32 v249, v128, v241
	s_waitcnt lgkmcnt(0)
	v_add_f32_e32 v234, v234, v242
	v_add_f32_e32 v235, v235, v243
	v_add_f32_e32 v236, v236, v244
	v_add_f32_e32 v237, v237, v245
	v_add_f32_e32 v238, v238, v246
	v_add_f32_e32 v239, v239, v247
	v_add_f32_e32 v240, v240, v248
	v_add_f32_e32 v241, v241, v249
	ds_bpermute_b32 v242, v199, v234
	ds_bpermute_b32 v243, v199, v235
	ds_bpermute_b32 v244, v199, v236
	ds_bpermute_b32 v245, v199, v237
	ds_bpermute_b32 v246, v199, v238
	ds_bpermute_b32 v247, v199, v239
	ds_bpermute_b32 v248, v199, v240
	ds_bpermute_b32 v249, v199, v241
	s_waitcnt lgkmcnt(0)
	v_add_f32_e32 v234, v234, v242
	v_add_f32_e32 v235, v235, v243
	v_add_f32_e32 v236, v236, v244
	v_add_f32_e32 v237, v237, v245
	v_add_f32_e32 v238, v238, v246
	v_add_f32_e32 v239, v239, v247
	v_add_f32_e32 v240, v240, v248
	v_add_f32_e32 v241, v241, v249
	v_fmamk_f32 v234, v234, 0x3a800000, v171
	v_cmp_gt_f32_e32 vcc, s11, v234
	v_mul_f32_e32 v242, 0x4b800000, v234
	s_nop 0
	v_cndmask_b32_e32 v234, v234, v242, vcc
	v_rsq_f32_e32 v234, v234
	s_nop 0
	v_mul_f32_e32 v242, 0x45800000, v234
	v_cndmask_b32_e32 v208, v234, v242, vcc
	v_fmamk_f32 v235, v235, 0x3a800000, v171
	v_cmp_gt_f32_e32 vcc, s11, v235
	v_mul_f32_e32 v243, 0x4b800000, v235
	s_nop 0
	v_cndmask_b32_e32 v235, v235, v243, vcc
	v_rsq_f32_e32 v235, v235
	s_nop 0
	v_mul_f32_e32 v243, 0x45800000, v235
	v_cndmask_b32_e32 v210, v235, v243, vcc
	v_fmamk_f32 v236, v236, 0x3a800000, v171
	v_cmp_gt_f32_e32 vcc, s11, v236
	v_mul_f32_e32 v244, 0x4b800000, v236
	s_nop 0
	v_cndmask_b32_e32 v236, v236, v244, vcc
	v_rsq_f32_e32 v236, v236
	s_nop 0
	v_mul_f32_e32 v244, 0x45800000, v236
	v_cndmask_b32_e32 v212, v236, v244, vcc
	v_fmamk_f32 v237, v237, 0x3a800000, v171
	v_cmp_gt_f32_e32 vcc, s11, v237
	v_mul_f32_e32 v245, 0x4b800000, v237
	s_nop 0
	v_cndmask_b32_e32 v237, v237, v245, vcc
	v_rsq_f32_e32 v237, v237
	s_nop 0
	v_mul_f32_e32 v245, 0x45800000, v237
	v_cndmask_b32_e32 v214, v237, v245, vcc
	v_fmamk_f32 v238, v238, 0x3a800000, v171
	v_cmp_gt_f32_e32 vcc, s11, v238
	v_mul_f32_e32 v246, 0x4b800000, v238
	s_nop 0
	v_cndmask_b32_e32 v238, v238, v246, vcc
; __device__ __forceinline__ unsigned pk2(float lo, float hi) { return pg8::cvt_pk_bf16(lo, hi); }
;     __device__ __forceinline__ void operator()(const pg8::f32x4 (&acc)[2][2][4][2], const pg8::Unit& u, int wr, int wc, int fr, int fq) const {
;     ...
; #pragma unroll
;         for (int ai = 0; ai < 2; ++ai)
; #pragma unroll
;             for (int m = 0; m < 4; ++m) {
;                 const size_t row = (size_t)(row0 + ai * 128 + m * 16);
;                 const float rs = row_rs4(ssq, row + row_off, fq);
; #pragma unroll
;                 for (int bj = 0; bj < 2; ++bj) {
;                     const pg8::f32x4 v0 = acc[ai][bj][m][0] * rs, v1 = acc[ai][bj][m][1] * rs;
;                     u32x4 w; w.x = pk2(v0[0], v0[1]); w.y = pk2(v0[2], v0[3]); w.z = pk2(v1[0], v1[1]); w.w = pk2(v1[2], v1[3]);
;                     *(u32x4*)(P + row * PLD + col0 + bj * 128) = w;
;                 }
;                 asm volatile("" ::: "memory");
;             }
	v_rsq_f32_e32 v238, v238
	s_nop 0
	v_mul_f32_e32 v246, 0x45800000, v238
	v_cndmask_b32_e32 v216, v238, v246, vcc
	v_fmamk_f32 v239, v239, 0x3a800000, v171
	v_cmp_gt_f32_e32 vcc, s11, v239
	v_mul_f32_e32 v247, 0x4b800000, v239
	s_nop 0
	v_cndmask_b32_e32 v239, v239, v247, vcc
	v_rsq_f32_e32 v239, v239
	s_nop 0
	v_mul_f32_e32 v247, 0x45800000, v239
	v_cndmask_b32_e32 v218, v239, v247, vcc
	v_fmamk_f32 v240, v240, 0x3a800000, v171
	v_cmp_gt_f32_e32 vcc, s11, v240
	v_mul_f32_e32 v248, 0x4b800000, v240
	s_nop 0
	v_cndmask_b32_e32 v240, v240, v248, vcc
	v_rsq_f32_e32 v240, v240
	s_nop 0
	v_mul_f32_e32 v248, 0x45800000, v240
	v_cndmask_b32_e32 v220, v240, v248, vcc
	v_fmamk_f32 v241, v241, 0x3a800000, v171
	v_cmp_gt_f32_e32 vcc, s11, v241
	v_mul_f32_e32 v249, 0x4b800000, v241
	s_nop 0
	v_cndmask_b32_e32 v241, v241, v249, vcc
	v_rsq_f32_e32 v241, v241
	s_nop 0
	v_mul_f32_e32 v249, 0x45800000, v241
	v_cndmask_b32_e32 v222, v241, v249, vcc
	v_mad_i64_i32 v[178:179], s[0:1], v164, s57, v[166:167]
	v_lshl_add_u64 v[176:177], v[178:179], 0, v[168:169]
	v_pk_mul_f32 v[200:201], v[124:125], v[208:209] op_sel_hi:[1,0]
	v_pk_mul_f32 v[202:203], v[126:127], v[208:209] op_sel_hi:[1,0]
	v_pk_mul_f32 v[204:205], v[116:117], v[208:209] op_sel_hi:[1,0]
	v_pk_mul_f32 v[206:207], v[118:119], v[208:209] op_sel_hi:[1,0]
	v_cvt_pk_bf16_f32 v242, v200, v201
	v_cvt_pk_bf16_f32 v243, v202, v203
	v_cvt_pk_bf16_f32 v244, v204, v205
	v_cvt_pk_bf16_f32 v245, v206, v207
	global_store_dwordx4 v[176:177], v[242:245], off
	v_pk_mul_f32 v[200:201], v[120:121], v[208:209] op_sel_hi:[1,0]
	v_pk_mul_f32 v[202:203], v[122:123], v[208:209] op_sel_hi:[1,0]
	v_pk_mul_f32 v[204:205], v[112:113], v[208:209] op_sel_hi:[1,0]
	v_pk_mul_f32 v[206:207], v[114:115], v[208:209] op_sel_hi:[1,0]
	v_cvt_pk_bf16_f32 v246, v200, v201
	v_cvt_pk_bf16_f32 v247, v202, v203
	v_cvt_pk_bf16_f32 v248, v204, v205
	v_cvt_pk_bf16_f32 v249, v206, v207
	global_store_dwordx4 v[176:177], v[246:249], off offset:256
	v_mad_i64_i32 v[178:179], s[0:1], v162, s57, v[166:167]
	v_lshl_add_u64 v[176:177], v[178:179], 0, v[168:169]
	v_pk_mul_f32 v[200:201], v[108:109], v[210:211] op_sel_hi:[1,0]
	v_pk_mul_f32 v[202:203], v[110:111], v[210:211] op_sel_hi:[1,0]
	v_pk_mul_f32 v[204:205], v[100:101], v[210:211] op_sel_hi:[1,0]
	v_pk_mul_f32 v[206:207], v[102:103], v[210:211] op_sel_hi:[1,0]
	v_cvt_pk_bf16_f32 v242, v200, v201
	v_cvt_pk_bf16_f32 v243, v202, v203
	v_cvt_pk_bf16_f32 v244, v204, v205
	v_cvt_pk_bf16_f32 v245, v206, v207
	global_store_dwordx4 v[176:177], v[242:245], off
	v_pk_mul_f32 v[200:201], v[104:105], v[210:211] op_sel_hi:[1,0]
	v_pk_mul_f32 v[202:203], v[106:107], v[210:211] op_sel_hi:[1,0]
	v_pk_mul_f32 v[204:205], v[96:97], v[210:211] op_sel_hi:[1,0]
	v_pk_mul_f32 v[206:207], v[98:99], v[210:211] op_sel_hi:[1,0]
	v_cvt_pk_bf16_f32 v246, v200, v201
	v_cvt_pk_bf16_f32 v247, v202, v203
	v_cvt_pk_bf16_f32 v248, v204, v205
	v_cvt_pk_bf16_f32 v249, v206, v207
	global_store_dwordx4 v[176:177], v[246:249], off offset:256
	v_mad_i64_i32 v[178:179], s[0:1], v160, s57, v[166:167]
	v_lshl_add_u64 v[176:177], v[178:179], 0, v[168:169]
	v_pk_mul_f32 v[200:201], v[92:93], v[212:213] op_sel_hi:[1,0]
	v_pk_mul_f32 v[202:203], v[94:95], v[212:213] op_sel_hi:[1,0]
	v_pk_mul_f32 v[204:205], v[84:85], v[212:213] op_sel_hi:[1,0]
	v_pk_mul_f32 v[206:207], v[86:87], v[212:213] op_sel_hi:[1,0]
	v_cvt_pk_bf16_f32 v242, v200, v201
	v_cvt_pk_bf16_f32 v243, v202, v203
	v_cvt_pk_bf16_f32 v244, v204, v205
	v_cvt_pk_bf16_f32 v245, v206, v207
	global_store_dwordx4 v[176:177], v[242:245], off
	v_pk_mul_f32 v[200:201], v[88:89], v[212:213] op_sel_hi:[1,0]
	v_pk_mul_f32 v[202:203], v[90:91], v[212:213] op_sel_hi:[1,0]
	v_pk_mul_f32 v[204:205], v[80:81], v[212:213] op_sel_hi:[1,0]
	v_pk_mul_f32 v[206:207], v[82:83], v[212:213] op_sel_hi:[1,0]
	v_cvt_pk_bf16_f32 v246, v200, v201
	v_cvt_pk_bf16_f32 v247, v202, v203
	v_cvt_pk_bf16_f32 v248, v204, v205
	v_cvt_pk_bf16_f32 v249, v206, v207
	global_store_dwordx4 v[176:177], v[246:249], off offset:256
	v_mad_i64_i32 v[178:179], s[0:1], v158, s57, v[166:167]
	v_lshl_add_u64 v[176:177], v[178:179], 0, v[168:169]
	v_pk_mul_f32 v[200:201], v[76:77], v[214:215] op_sel_hi:[1,0]
	v_pk_mul_f32 v[202:203], v[78:79], v[214:215] op_sel_hi:[1,0]
	v_pk_mul_f32 v[204:205], v[68:69], v[214:215] op_sel_hi:[1,0]
	v_pk_mul_f32 v[206:207], v[70:71], v[214:215] op_sel_hi:[1,0]
	v_cvt_pk_bf16_f32 v242, v200, v201
	v_cvt_pk_bf16_f32 v243, v202, v203
	v_cvt_pk_bf16_f32 v244, v204, v205
	v_cvt_pk_bf16_f32 v245, v206, v207
; __device__ __forceinline__ unsigned pk2(float lo, float hi) { return pg8::cvt_pk_bf16(lo, hi); }
;     __device__ __forceinline__ void operator()(const pg8::f32x4 (&acc)[2][2][4][2], const pg8::Unit& u, int wr, int wc, int fr, int fq) const {
;     ...
; #pragma unroll
;         for (int ai = 0; ai < 2; ++ai)
; #pragma unroll
;             for (int m = 0; m < 4; ++m) {
;                 const size_t row = (size_t)(row0 + ai * 128 + m * 16);
;                 const float rs = row_rs4(ssq, row + row_off, fq);
; #pragma unroll
;                 for (int bj = 0; bj < 2; ++bj) {
;                     const pg8::f32x4 v0 = acc[ai][bj][m][0] * rs, v1 = acc[ai][bj][m][1] * rs;
;                     u32x4 w; w.x = pk2(v0[0], v0[1]); w.y = pk2(v0[2], v0[3]); w.z = pk2(v1[0], v1[1]); w.w = pk2(v1[2], v1[3]);
;                     *(u32x4*)(P + row * PLD + col0 + bj * 128) = w;
;                 }
;                 asm volatile("" ::: "memory");
;             }
	global_store_dwordx4 v[176:177], v[242:245], off
	v_pk_mul_f32 v[200:201], v[72:73], v[214:215] op_sel_hi:[1,0]
	v_pk_mul_f32 v[202:203], v[74:75], v[214:215] op_sel_hi:[1,0]
	v_pk_mul_f32 v[204:205], v[64:65], v[214:215] op_sel_hi:[1,0]
	v_pk_mul_f32 v[206:207], v[66:67], v[214:215] op_sel_hi:[1,0]
	v_cvt_pk_bf16_f32 v246, v200, v201
	v_cvt_pk_bf16_f32 v247, v202, v203
	v_cvt_pk_bf16_f32 v248, v204, v205
	v_cvt_pk_bf16_f32 v249, v206, v207
	global_store_dwordx4 v[176:177], v[246:249], off offset:256
	v_mad_i64_i32 v[178:179], s[0:1], v156, s57, v[166:167]
	v_lshl_add_u64 v[176:177], v[178:179], 0, v[168:169]
	v_pk_mul_f32 v[200:201], v[60:61], v[216:217] op_sel_hi:[1,0]
	v_pk_mul_f32 v[202:203], v[62:63], v[216:217] op_sel_hi:[1,0]
	v_pk_mul_f32 v[204:205], v[52:53], v[216:217] op_sel_hi:[1,0]
	v_pk_mul_f32 v[206:207], v[54:55], v[216:217] op_sel_hi:[1,0]
	v_cvt_pk_bf16_f32 v242, v200, v201
	v_cvt_pk_bf16_f32 v243, v202, v203
	v_cvt_pk_bf16_f32 v244, v204, v205
	v_cvt_pk_bf16_f32 v245, v206, v207
	global_store_dwordx4 v[176:177], v[242:245], off
	v_pk_mul_f32 v[200:201], v[56:57], v[216:217] op_sel_hi:[1,0]
	v_pk_mul_f32 v[202:203], v[58:59], v[216:217] op_sel_hi:[1,0]
	v_pk_mul_f32 v[204:205], v[48:49], v[216:217] op_sel_hi:[1,0]
	v_pk_mul_f32 v[206:207], v[50:51], v[216:217] op_sel_hi:[1,0]
	v_cvt_pk_bf16_f32 v246, v200, v201
	v_cvt_pk_bf16_f32 v247, v202, v203
	v_cvt_pk_bf16_f32 v248, v204, v205
	v_cvt_pk_bf16_f32 v249, v206, v207
	global_store_dwordx4 v[176:177], v[246:249], off offset:256
	v_mad_i64_i32 v[178:179], s[0:1], v154, s57, v[166:167]
	v_lshl_add_u64 v[176:177], v[178:179], 0, v[168:169]
	v_pk_mul_f32 v[200:201], v[44:45], v[218:219] op_sel_hi:[1,0]
	v_pk_mul_f32 v[202:203], v[46:47], v[218:219] op_sel_hi:[1,0]
	v_pk_mul_f32 v[204:205], v[36:37], v[218:219] op_sel_hi:[1,0]
	v_pk_mul_f32 v[206:207], v[38:39], v[218:219] op_sel_hi:[1,0]
	v_cvt_pk_bf16_f32 v242, v200, v201
	v_cvt_pk_bf16_f32 v243, v202, v203
	v_cvt_pk_bf16_f32 v244, v204, v205
	v_cvt_pk_bf16_f32 v245, v206, v207
	global_store_dwordx4 v[176:177], v[242:245], off
	v_pk_mul_f32 v[200:201], v[40:41], v[218:219] op_sel_hi:[1,0]
	v_pk_mul_f32 v[202:203], v[42:43], v[218:219] op_sel_hi:[1,0]
	v_pk_mul_f32 v[204:205], v[32:33], v[218:219] op_sel_hi:[1,0]
	v_pk_mul_f32 v[206:207], v[34:35], v[218:219] op_sel_hi:[1,0]
	v_cvt_pk_bf16_f32 v246, v200, v201
	v_cvt_pk_bf16_f32 v247, v202, v203
	v_cvt_pk_bf16_f32 v248, v204, v205
	v_cvt_pk_bf16_f32 v249, v206, v207
	global_store_dwordx4 v[176:177], v[246:249], off offset:256
	v_mad_i64_i32 v[178:179], s[0:1], v152, s57, v[166:167]
	v_lshl_add_u64 v[176:177], v[178:179], 0, v[168:169]
	v_pk_mul_f32 v[200:201], v[28:29], v[220:221] op_sel_hi:[1,0]
	v_pk_mul_f32 v[202:203], v[30:31], v[220:221] op_sel_hi:[1,0]
	v_pk_mul_f32 v[204:205], v[20:21], v[220:221] op_sel_hi:[1,0]
	v_pk_mul_f32 v[206:207], v[22:23], v[220:221] op_sel_hi:[1,0]
	v_cvt_pk_bf16_f32 v242, v200, v201
	v_cvt_pk_bf16_f32 v243, v202, v203
	v_cvt_pk_bf16_f32 v244, v204, v205
	v_cvt_pk_bf16_f32 v245, v206, v207
	global_store_dwordx4 v[176:177], v[242:245], off
	v_pk_mul_f32 v[200:201], v[24:25], v[220:221] op_sel_hi:[1,0]
	v_pk_mul_f32 v[202:203], v[26:27], v[220:221] op_sel_hi:[1,0]
	v_pk_mul_f32 v[204:205], v[16:17], v[220:221] op_sel_hi:[1,0]
	v_pk_mul_f32 v[206:207], v[18:19], v[220:221] op_sel_hi:[1,0]
	v_cvt_pk_bf16_f32 v246, v200, v201
	v_cvt_pk_bf16_f32 v247, v202, v203
	v_cvt_pk_bf16_f32 v248, v204, v205
	v_cvt_pk_bf16_f32 v249, v206, v207
	global_store_dwordx4 v[176:177], v[246:249], off offset:256
	v_mad_i64_i32 v[178:179], s[0:1], v150, s57, v[166:167]
	v_lshl_add_u64 v[176:177], v[178:179], 0, v[168:169]
	v_pk_mul_f32 v[200:201], v[12:13], v[222:223] op_sel_hi:[1,0]
	v_pk_mul_f32 v[202:203], v[14:15], v[222:223] op_sel_hi:[1,0]
	v_pk_mul_f32 v[204:205], v[4:5], v[222:223] op_sel_hi:[1,0]
	v_pk_mul_f32 v[206:207], v[6:7], v[222:223] op_sel_hi:[1,0]
	v_cvt_pk_bf16_f32 v242, v200, v201
	v_cvt_pk_bf16_f32 v243, v202, v203
	v_cvt_pk_bf16_f32 v244, v204, v205
	v_cvt_pk_bf16_f32 v245, v206, v207
	global_store_dwordx4 v[176:177], v[242:245], off
	v_pk_mul_f32 v[200:201], v[8:9], v[222:223] op_sel_hi:[1,0]
	v_pk_mul_f32 v[202:203], v[10:11], v[222:223] op_sel_hi:[1,0]
	v_pk_mul_f32 v[204:205], v[0:1], v[222:223] op_sel_hi:[1,0]
	v_pk_mul_f32 v[206:207], v[2:3], v[222:223] op_sel_hi:[1,0]
	v_cvt_pk_bf16_f32 v246, v200, v201
	v_cvt_pk_bf16_f32 v247, v202, v203
	v_cvt_pk_bf16_f32 v248, v204, v205
	v_cvt_pk_bf16_f32 v249, v206, v207
	global_store_dwordx4 v[176:177], v[246:249], off offset:256
	s_branch .LBB0_180

; #define LAS __attribute__((address_space(3)))
; __device__ __forceinline__ unsigned pk2(float lo, float hi) { return pg8::cvt_pk_bf16(lo, hi); }
; __device__ __forceinline__ void ssd_item(LAS unsigned char* lds, const bf16* proj, const bf16* cxb, bf16* yout, const float* dt_bias, const float* a_log, const float* dskip,
;                                          int gv, int vloc, int hh, int dir) {
;     ...
;             const float x0 = DT[2 * lane] * aneg, x1 = DT[2 * lane + 1] * aneg;
;             float s = x0 + x1;
; #pragma unroll
;             for (int o = 1; o < 64; o <<= 1) { const float t = __shfl_up(s, o); if (lane >= o) s += t; }
;             tot = __shfl(s, 63);
;             const float p1 = s, p0 = s - x1;
;             if (dir == 0) { ACUM[2 * lane] = p0; ACUM[2 * lane + 1] = p1; }
;             else { ACUM[2 * lane] = tot - p0 + x0; ACUM[2 * lane + 1] = tot - p1 + x1; }
;         }
;         if (stager) {
; #pragma unroll
;             for (int hc = 0; hc < 2; ++hc) {
;                 u32x2 pv[4];
; #pragma unroll
;                 for (int od = 0; od < 8; ++od) {
;                     u32x2 pk; pk.x = raw[od][2 * hc]; pk.y = raw[od][2 * hc + 1];
;                     if (sec == 0) pv[od & 3] = pk;
;                     else if (sec == 1) { *(LAS u32x2*)(BN + (i0 + od) * LDS_ + c8 + 4 * hc) = pk; const float wr = __expf(tot - ACUM[i0 + od]) * DT[i0 + od];
;                         u32x2 pw; pw.x = pk2(bflo(pk.x) * wr, bfhi(pk.x) * wr); pw.y = pk2(bflo(pk.y) * wr, bfhi(pk.y) * wr); pv[od & 3] = pw; }
;                     else *(LAS u32x2*)(CN + (i0 + od) * LDS_ + c8 + 4 * hc) = pk;
.LBB0_500:
	s_or_b64 exec, exec, s[0:1]
	s_waitcnt lgkmcnt(0)
	s_barrier
	ds_read_b64 v[32:33], v70
	v_readlane_b32 s0, v254, 55
	v_readlane_b32 s1, v254, 56
	s_waitcnt lgkmcnt(0)
	v_pk_mul_f32 v[34:35], v[32:33], v[54:55]
	s_nop 0
	v_add_f32_e32 v34, v34, v35
	ds_bpermute_b32 v36, v83, v34
	s_waitcnt lgkmcnt(0)
	v_add_f32_e32 v36, v34, v36
	v_cndmask_b32_e64 v34, v36, v34, s[0:1]
	ds_bpermute_b32 v36, v84, v34
	v_readlane_b32 s0, v254, 57
	v_readlane_b32 s1, v254, 58
	s_waitcnt lgkmcnt(0)
	v_add_f32_e32 v36, v34, v36
	v_cndmask_b32_e64 v34, v36, v34, s[0:1]
	ds_bpermute_b32 v36, v85, v34
	v_readlane_b32 s0, v254, 59
	v_readlane_b32 s1, v254, 60
	s_waitcnt lgkmcnt(0)
	v_add_f32_e32 v36, v34, v36
	v_cndmask_b32_e64 v34, v36, v34, s[0:1]
	ds_bpermute_b32 v36, v86, v34
	v_readlane_b32 s0, v254, 61
	v_readlane_b32 s1, v254, 62
	s_waitcnt lgkmcnt(0)
	v_add_f32_e32 v36, v34, v36
	v_cndmask_b32_e64 v34, v36, v34, s[0:1]
	ds_bpermute_b32 v36, v87, v34
	v_readlane_b32 s0, v254, 63
	v_readlane_b32 s1, v255, 0
	s_waitcnt lgkmcnt(0)
	v_add_f32_e32 v36, v34, v36
	v_cndmask_b32_e64 v34, v36, v34, s[0:1]
	ds_bpermute_b32 v36, v88, v34
	s_waitcnt lgkmcnt(0)
	v_add_f32_e32 v36, v34, v36
	v_cndmask_b32_e64 v37, v36, v34, s[60:61]
	ds_bpermute_b32 v64, v72, v37
	v_sub_f32_e32 v36, v37, v35
	s_waitcnt lgkmcnt(0)
	v_pk_add_f32 v[34:35], v[64:65], v[36:37] op_sel_hi:[0,1] neg_lo:[0,1] neg_hi:[0,1]
	v_pk_fma_f32 v[32:33], v[32:33], v[54:55], v[34:35]
	s_nop 0
	v_cndmask_b32_e64 v33, v33, v37, s[38:39]
	v_cndmask_b32_e64 v32, v32, v36, s[38:39]
	ds_write_b64 v74, v[32:33]
	ds_read_b32 v156, v90
	ds_read_b32 v157, v93
	ds_read_b32 v158, v95
	ds_read_b32 v159, v97
	ds_read_b32 v160, v99
	ds_read_b32 v161, v101
	ds_read_b32 v162, v103
	ds_read_b32 v163, v105
	ds_read_b32 v164, v91
	ds_read_b32 v165, v94
	ds_read_b32 v166, v96
	ds_read_b32 v167, v98
	ds_read_b32 v228, v100
	ds_read_b32 v229, v102
	ds_read_b32 v230, v104
	s_waitcnt lgkmcnt(7)
	v_sub_f32_e32 v156, v64, v156
	v_sub_f32_e32 v157, v64, v157
	v_sub_f32_e32 v158, v64, v158
	v_sub_f32_e32 v159, v64, v159
	v_sub_f32_e32 v160, v64, v160
	v_sub_f32_e32 v161, v64, v161
	v_sub_f32_e32 v162, v64, v162
	v_sub_f32_e32 v163, v64, v163
	ds_read_b32 v231, v106
	v_mul_f32_e32 v156, 0x3fb8aa3b, v156
	v_mul_f32_e32 v157, 0x3fb8aa3b, v157
	v_mul_f32_e32 v158, 0x3fb8aa3b, v158
	v_mul_f32_e32 v159, 0x3fb8aa3b, v159
	v_mul_f32_e32 v160, 0x3fb8aa3b, v160
	v_mul_f32_e32 v161, 0x3fb8aa3b, v161
	v_mul_f32_e32 v162, 0x3fb8aa3b, v162
	v_mul_f32_e32 v163, 0x3fb8aa3b, v163
	v_exp_f32_e32 v156, v156
	v_exp_f32_e32 v157, v157
	v_exp_f32_e32 v158, v158
	v_exp_f32_e32 v159, v159
	v_exp_f32_e32 v160, v160
	v_exp_f32_e32 v161, v161
	v_exp_f32_e32 v162, v162
	v_exp_f32_e32 v163, v163
	s_waitcnt lgkmcnt(0)
	v_mul_f32_e32 v156, v164, v156
	v_mul_f32_e32 v157, v165, v157
	v_mul_f32_e32 v158, v166, v158
	v_mul_f32_e32 v159, v167, v159
	v_mul_f32_e32 v160, v228, v160
	v_mul_f32_e32 v161, v229, v161
	v_mul_f32_e32 v162, v230, v162
	v_mul_f32_e32 v163, v231, v163
	s_and_saveexec_b64 vcc, s[42:43]
	s_cbranch_execz .LBB0_539
	s_and_saveexec_b64 s[0:1], s[40:41]
	s_xor_b64 s[0:1], exec, s[0:1]
	s_cbranch_execnz .LBB0_553
	s_andn2_saveexec_b64 s[0:1], s[0:1]
	s_cbranch_execnz .LBB0_558

; #define LAS __attribute__((address_space(3)))
; __device__ __forceinline__ unsigned pk2(float lo, float hi) { return pg8::cvt_pk_bf16(lo, hi); }
; __device__ __forceinline__ void ssd_item(LAS unsigned char* lds, const bf16* proj, const bf16* cxb, bf16* yout, const float* dt_bias, const float* a_log, const float* dskip,
;                                          int gv, int vloc, int hh, int dir) {
;     ...
;                     u32x2 pk; pk.x = raw[od][2 * hc]; pk.y = raw[od][2 * hc + 1];
;                     if (sec == 0) pv[od & 3] = pk;
;                     else if (sec == 1) { *(LAS u32x2*)(BN + (i0 + od) * LDS_ + c8 + 4 * hc) = pk; const float wr = __expf(tot - ACUM[i0 + od]) * DT[i0 + od];
;                         u32x2 pw; pw.x = pk2(bflo(pk.x) * wr, bfhi(pk.x) * wr); pw.y = pk2(bflo(pk.y) * wr, bfhi(pk.y) * wr); pv[od & 3] = pw; }
.LBB0_555:
	s_andn2_saveexec_b64 s[50:51], s[50:51]
	s_cbranch_execz .LBB0_557
	v_add_u32_e32 v32, v75, v89
	s_waitcnt vmcnt(11)
	ds_write_b64 v32, v[0:1] offset:35840
	v_and_b32_e32 v34, 0xffff0000, v0
	v_mov_b32_e32 v32, v156
	v_lshlrev_b32_e32 v33, 16, v0
	v_mul_f32_e32 v33, v32, v33
	v_mul_f32_e32 v34, v32, v34
	v_cvt_pk_bf16_f32 v113, v33, v34
	v_lshlrev_b32_e32 v33, 16, v1
	v_and_b32_e32 v34, 0xffff0000, v1
	v_mul_f32_e32 v33, v32, v33
	v_mul_f32_e32 v32, v32, v34
	v_cvt_pk_bf16_f32 v140, v33, v32

; #define LAS __attribute__((address_space(3)))
; __device__ __forceinline__ unsigned pk2(float lo, float hi) { return pg8::cvt_pk_bf16(lo, hi); }
; __device__ __forceinline__ void ssd_item(LAS unsigned char* lds, const bf16* proj, const bf16* cxb, bf16* yout, const float* dt_bias, const float* a_log, const float* dskip,
;                                          int gv, int vloc, int hh, int dir) {
;     ...
;                     u32x2 pk; pk.x = raw[od][2 * hc]; pk.y = raw[od][2 * hc + 1];
;                     if (sec == 0) pv[od & 3] = pk;
;                     else if (sec == 1) { *(LAS u32x2*)(BN + (i0 + od) * LDS_ + c8 + 4 * hc) = pk; const float wr = __expf(tot - ACUM[i0 + od]) * DT[i0 + od];
;                         u32x2 pw; pw.x = pk2(bflo(pk.x) * wr, bfhi(pk.x) * wr); pw.y = pk2(bflo(pk.y) * wr, bfhi(pk.y) * wr); pv[od & 3] = pw; }
.LBB0_561:
	s_andn2_saveexec_b64 s[50:51], s[50:51]
	s_cbranch_execz .LBB0_563
	v_add_u32_e32 v32, v75, v92
	s_waitcnt vmcnt(10)
	ds_write_b64 v32, v[4:5] offset:35840
	v_and_b32_e32 v34, 0xffff0000, v4
	v_mov_b32_e32 v32, v157
	v_lshlrev_b32_e32 v33, 16, v4
	v_mul_f32_e32 v33, v32, v33
	v_mul_f32_e32 v34, v32, v34
	v_cvt_pk_bf16_f32 v137, v33, v34
	v_lshlrev_b32_e32 v33, 16, v5
	v_and_b32_e32 v34, 0xffff0000, v5
	v_mul_f32_e32 v33, v32, v33
	v_mul_f32_e32 v32, v32, v34
	v_cvt_pk_bf16_f32 v141, v33, v32

; #define LAS __attribute__((address_space(3)))
; __device__ __forceinline__ unsigned pk2(float lo, float hi) { return pg8::cvt_pk_bf16(lo, hi); }
; __device__ __forceinline__ void ssd_item(LAS unsigned char* lds, const bf16* proj, const bf16* cxb, bf16* yout, const float* dt_bias, const float* a_log, const float* dskip,
;                                          int gv, int vloc, int hh, int dir) {
;     ...
;                     u32x2 pk; pk.x = raw[od][2 * hc]; pk.y = raw[od][2 * hc + 1];
;                     if (sec == 0) pv[od & 3] = pk;
;                     else if (sec == 1) { *(LAS u32x2*)(BN + (i0 + od) * LDS_ + c8 + 4 * hc) = pk; const float wr = __expf(tot - ACUM[i0 + od]) * DT[i0 + od];
;                         u32x2 pw; pw.x = pk2(bflo(pk.x) * wr, bfhi(pk.x) * wr); pw.y = pk2(bflo(pk.y) * wr, bfhi(pk.y) * wr); pv[od & 3] = pw; }
.LBB0_567:
	s_andn2_saveexec_b64 s[50:51], s[50:51]
	s_cbranch_execz .LBB0_569
	v_add_u32_e32 v32, v75, v92
	s_waitcnt vmcnt(9)
	ds_write_b64 v32, v[8:9] offset:35984
	v_and_b32_e32 v34, 0xffff0000, v8
	v_mov_b32_e32 v32, v158
	v_lshlrev_b32_e32 v33, 16, v8
	v_mul_f32_e32 v33, v32, v33
	v_mul_f32_e32 v34, v32, v34
	v_cvt_pk_bf16_f32 v138, v33, v34
	v_lshlrev_b32_e32 v33, 16, v9
	v_and_b32_e32 v34, 0xffff0000, v9
	v_mul_f32_e32 v33, v32, v33
	v_mul_f32_e32 v32, v32, v34
	v_cvt_pk_bf16_f32 v142, v33, v32

; #define LAS __attribute__((address_space(3)))
; __device__ __forceinline__ unsigned pk2(float lo, float hi) { return pg8::cvt_pk_bf16(lo, hi); }
; __device__ __forceinline__ void ssd_item(LAS unsigned char* lds, const bf16* proj, const bf16* cxb, bf16* yout, const float* dt_bias, const float* a_log, const float* dskip,
;                                          int gv, int vloc, int hh, int dir) {
;     ...
;                     u32x2 pk; pk.x = raw[od][2 * hc]; pk.y = raw[od][2 * hc + 1];
;                     if (sec == 0) pv[od & 3] = pk;
;                     else if (sec == 1) { *(LAS u32x2*)(BN + (i0 + od) * LDS_ + c8 + 4 * hc) = pk; const float wr = __expf(tot - ACUM[i0 + od]) * DT[i0 + od];
;                         u32x2 pw; pw.x = pk2(bflo(pk.x) * wr, bfhi(pk.x) * wr); pw.y = pk2(bflo(pk.y) * wr, bfhi(pk.y) * wr); pv[od & 3] = pw; }
.LBB0_573:
	s_andn2_saveexec_b64 s[50:51], s[50:51]
	s_cbranch_execz .LBB0_575
	v_add_u32_e32 v32, v75, v92
	s_waitcnt vmcnt(8)
	ds_write_b64 v32, v[12:13] offset:36128
	v_and_b32_e32 v34, 0xffff0000, v12
	v_mov_b32_e32 v32, v159
	v_lshlrev_b32_e32 v33, 16, v12
	v_mul_f32_e32 v33, v32, v33
	v_mul_f32_e32 v34, v32, v34
	v_cvt_pk_bf16_f32 v139, v33, v34
	v_lshlrev_b32_e32 v33, 16, v13
	v_and_b32_e32 v34, 0xffff0000, v13
	v_mul_f32_e32 v33, v32, v33
	v_mul_f32_e32 v32, v32, v34
	v_cvt_pk_bf16_f32 v143, v33, v32

; #define LAS __attribute__((address_space(3)))
; __device__ __forceinline__ unsigned pk2(float lo, float hi) { return pg8::cvt_pk_bf16(lo, hi); }
; __device__ __forceinline__ void ssd_item(LAS unsigned char* lds, const bf16* proj, const bf16* cxb, bf16* yout, const float* dt_bias, const float* a_log, const float* dskip,
;                                          int gv, int vloc, int hh, int dir) {
;     ...
;                     u32x2 pk; pk.x = raw[od][2 * hc]; pk.y = raw[od][2 * hc + 1];
;                     if (sec == 0) pv[od & 3] = pk;
;                     else if (sec == 1) { *(LAS u32x2*)(BN + (i0 + od) * LDS_ + c8 + 4 * hc) = pk; const float wr = __expf(tot - ACUM[i0 + od]) * DT[i0 + od];
;                         u32x2 pw; pw.x = pk2(bflo(pk.x) * wr, bfhi(pk.x) * wr); pw.y = pk2(bflo(pk.y) * wr, bfhi(pk.y) * wr); pv[od & 3] = pw; }
.LBB0_580:
	s_andn2_saveexec_b64 s[50:51], s[50:51]
	s_cbranch_execz .LBB0_582
	v_add_u32_e32 v32, v75, v92
	s_waitcnt vmcnt(7)
	ds_write_b64 v32, v[16:17] offset:36272
	v_and_b32_e32 v34, 0xffff0000, v16
	v_mov_b32_e32 v32, v160
	v_lshlrev_b32_e32 v33, 16, v16
	v_mul_f32_e32 v33, v32, v33
	v_mul_f32_e32 v34, v32, v34
	v_cvt_pk_bf16_f32 v113, v33, v34
	v_lshlrev_b32_e32 v33, 16, v17
	v_and_b32_e32 v34, 0xffff0000, v17
	v_mul_f32_e32 v33, v32, v33
	v_mul_f32_e32 v32, v32, v34
	v_cvt_pk_bf16_f32 v140, v33, v32

; #define LAS __attribute__((address_space(3)))
; __device__ __forceinline__ unsigned pk2(float lo, float hi) { return pg8::cvt_pk_bf16(lo, hi); }
; __device__ __forceinline__ void ssd_item(LAS unsigned char* lds, const bf16* proj, const bf16* cxb, bf16* yout, const float* dt_bias, const float* a_log, const float* dskip,
;                                          int gv, int vloc, int hh, int dir) {
;     ...
;                     u32x2 pk; pk.x = raw[od][2 * hc]; pk.y = raw[od][2 * hc + 1];
;                     if (sec == 0) pv[od & 3] = pk;
;                     else if (sec == 1) { *(LAS u32x2*)(BN + (i0 + od) * LDS_ + c8 + 4 * hc) = pk; const float wr = __expf(tot - ACUM[i0 + od]) * DT[i0 + od];
;                         u32x2 pw; pw.x = pk2(bflo(pk.x) * wr, bfhi(pk.x) * wr); pw.y = pk2(bflo(pk.y) * wr, bfhi(pk.y) * wr); pv[od & 3] = pw; }
.LBB0_586:
	s_andn2_saveexec_b64 s[50:51], s[50:51]
	s_cbranch_execz .LBB0_588
	v_add_u32_e32 v32, v75, v92
	s_waitcnt vmcnt(6)
	ds_write_b64 v32, v[20:21] offset:36416
	v_and_b32_e32 v34, 0xffff0000, v20
	v_mov_b32_e32 v32, v161
	v_lshlrev_b32_e32 v33, 16, v20
	v_mul_f32_e32 v33, v32, v33
	v_mul_f32_e32 v34, v32, v34
	v_cvt_pk_bf16_f32 v137, v33, v34
	v_lshlrev_b32_e32 v33, 16, v21
	v_and_b32_e32 v34, 0xffff0000, v21
	v_mul_f32_e32 v33, v32, v33
	v_mul_f32_e32 v32, v32, v34
	v_cvt_pk_bf16_f32 v141, v33, v32

; #define LAS __attribute__((address_space(3)))
; __device__ __forceinline__ unsigned pk2(float lo, float hi) { return pg8::cvt_pk_bf16(lo, hi); }
; __device__ __forceinline__ void ssd_item(LAS unsigned char* lds, const bf16* proj, const bf16* cxb, bf16* yout, const float* dt_bias, const float* a_log, const float* dskip,
;                                          int gv, int vloc, int hh, int dir) {
;     ...
;                     u32x2 pk; pk.x = raw[od][2 * hc]; pk.y = raw[od][2 * hc + 1];
;                     if (sec == 0) pv[od & 3] = pk;
;                     else if (sec == 1) { *(LAS u32x2*)(BN + (i0 + od) * LDS_ + c8 + 4 * hc) = pk; const float wr = __expf(tot - ACUM[i0 + od]) * DT[i0 + od];
;                         u32x2 pw; pw.x = pk2(bflo(pk.x) * wr, bfhi(pk.x) * wr); pw.y = pk2(bflo(pk.y) * wr, bfhi(pk.y) * wr); pv[od & 3] = pw; }
.LBB0_592:
	s_andn2_saveexec_b64 s[50:51], s[50:51]
	s_cbranch_execz .LBB0_594
	v_add_u32_e32 v32, v75, v92
	s_waitcnt vmcnt(5)
	ds_write_b64 v32, v[24:25] offset:36560
	v_and_b32_e32 v34, 0xffff0000, v24
	v_mov_b32_e32 v32, v162
	v_lshlrev_b32_e32 v33, 16, v24
	v_mul_f32_e32 v33, v32, v33
	v_mul_f32_e32 v34, v32, v34
	v_cvt_pk_bf16_f32 v138, v33, v34
	v_lshlrev_b32_e32 v33, 16, v25
	v_and_b32_e32 v34, 0xffff0000, v25
	v_mul_f32_e32 v33, v32, v33
	v_mul_f32_e32 v32, v32, v34
	v_cvt_pk_bf16_f32 v142, v33, v32

; #define LAS __attribute__((address_space(3)))
; __device__ __forceinline__ unsigned pk2(float lo, float hi) { return pg8::cvt_pk_bf16(lo, hi); }
; __device__ __forceinline__ void ssd_item(LAS unsigned char* lds, const bf16* proj, const bf16* cxb, bf16* yout, const float* dt_bias, const float* a_log, const float* dskip,
;                                          int gv, int vloc, int hh, int dir) {
;     ...
;                     u32x2 pk; pk.x = raw[od][2 * hc]; pk.y = raw[od][2 * hc + 1];
;                     if (sec == 0) pv[od & 3] = pk;
;                     else if (sec == 1) { *(LAS u32x2*)(BN + (i0 + od) * LDS_ + c8 + 4 * hc) = pk; const float wr = __expf(tot - ACUM[i0 + od]) * DT[i0 + od];
;                         u32x2 pw; pw.x = pk2(bflo(pk.x) * wr, bfhi(pk.x) * wr); pw.y = pk2(bflo(pk.y) * wr, bfhi(pk.y) * wr); pv[od & 3] = pw; }
.LBB0_598:
	s_andn2_saveexec_b64 s[50:51], s[50:51]
	s_cbranch_execz .LBB0_600
	v_add_u32_e32 v32, v75, v92
	s_waitcnt vmcnt(4)
	ds_write_b64 v32, v[28:29] offset:36704
	v_and_b32_e32 v34, 0xffff0000, v28
	v_mov_b32_e32 v32, v163
	v_lshlrev_b32_e32 v33, 16, v28
	v_mul_f32_e32 v33, v32, v33
	v_mul_f32_e32 v34, v32, v34
	v_cvt_pk_bf16_f32 v139, v33, v34
	v_lshlrev_b32_e32 v33, 16, v29
	v_and_b32_e32 v34, 0xffff0000, v29
	v_mul_f32_e32 v33, v32, v33
	v_mul_f32_e32 v32, v32, v34
	v_cvt_pk_bf16_f32 v143, v33, v32

; #define LAS __attribute__((address_space(3)))
; __device__ __forceinline__ unsigned pk2(float lo, float hi) { return pg8::cvt_pk_bf16(lo, hi); }
; __device__ __forceinline__ void ssd_item(LAS unsigned char* lds, const bf16* proj, const bf16* cxb, bf16* yout, const float* dt_bias, const float* a_log, const float* dskip,
;                                          int gv, int vloc, int hh, int dir) {
;     ...
;                     u32x2 pk; pk.x = raw[od][2 * hc]; pk.y = raw[od][2 * hc + 1];
;                     if (sec == 0) pv[od & 3] = pk;
;                     else if (sec == 1) { *(LAS u32x2*)(BN + (i0 + od) * LDS_ + c8 + 4 * hc) = pk; const float wr = __expf(tot - ACUM[i0 + od]) * DT[i0 + od];
;                         u32x2 pw; pw.x = pk2(bflo(pk.x) * wr, bfhi(pk.x) * wr); pw.y = pk2(bflo(pk.y) * wr, bfhi(pk.y) * wr); pv[od & 3] = pw; }
.LBB0_605:
	s_andn2_saveexec_b64 s[50:51], s[50:51]
	s_cbranch_execz .LBB0_607
	v_add_u32_e32 v32, v75, v89
	s_waitcnt vmcnt(11)
	ds_write_b64 v32, v[2:3] offset:35848
	v_and_b32_e32 v34, 0xffff0000, v2
	v_mov_b32_e32 v32, v156
	v_lshlrev_b32_e32 v33, 16, v2
	v_mul_f32_e32 v33, v32, v33
	v_mul_f32_e32 v34, v32, v34
	v_cvt_pk_bf16_f32 v113, v33, v34
	v_lshlrev_b32_e32 v33, 16, v3
	v_and_b32_e32 v34, 0xffff0000, v3
	v_mul_f32_e32 v33, v32, v33
	v_mul_f32_e32 v32, v32, v34
	v_cvt_pk_bf16_f32 v140, v33, v32

; #define LAS __attribute__((address_space(3)))
; __device__ __forceinline__ unsigned pk2(float lo, float hi) { return pg8::cvt_pk_bf16(lo, hi); }
; __device__ __forceinline__ void ssd_item(LAS unsigned char* lds, const bf16* proj, const bf16* cxb, bf16* yout, const float* dt_bias, const float* a_log, const float* dskip,
;                                          int gv, int vloc, int hh, int dir) {
;     ...
;                     u32x2 pk; pk.x = raw[od][2 * hc]; pk.y = raw[od][2 * hc + 1];
;                     if (sec == 0) pv[od & 3] = pk;
;                     else if (sec == 1) { *(LAS u32x2*)(BN + (i0 + od) * LDS_ + c8 + 4 * hc) = pk; const float wr = __expf(tot - ACUM[i0 + od]) * DT[i0 + od];
;                         u32x2 pw; pw.x = pk2(bflo(pk.x) * wr, bfhi(pk.x) * wr); pw.y = pk2(bflo(pk.y) * wr, bfhi(pk.y) * wr); pv[od & 3] = pw; }
.LBB0_611:
	s_andn2_saveexec_b64 s[50:51], s[50:51]
	s_cbranch_execz .LBB0_613
	v_add_u32_e32 v32, v75, v92
	s_waitcnt vmcnt(10)
	ds_write_b64 v32, v[6:7] offset:35848
	v_and_b32_e32 v34, 0xffff0000, v6
	v_mov_b32_e32 v32, v157
	v_lshlrev_b32_e32 v33, 16, v6
	v_mul_f32_e32 v33, v32, v33
	v_mul_f32_e32 v34, v32, v34
	v_cvt_pk_bf16_f32 v137, v33, v34
	v_lshlrev_b32_e32 v33, 16, v7
	v_and_b32_e32 v34, 0xffff0000, v7
	v_mul_f32_e32 v33, v32, v33
	v_mul_f32_e32 v32, v32, v34
	v_cvt_pk_bf16_f32 v141, v33, v32

; #define LAS __attribute__((address_space(3)))
; __device__ __forceinline__ unsigned pk2(float lo, float hi) { return pg8::cvt_pk_bf16(lo, hi); }
; __device__ __forceinline__ void ssd_item(LAS unsigned char* lds, const bf16* proj, const bf16* cxb, bf16* yout, const float* dt_bias, const float* a_log, const float* dskip,
;                                          int gv, int vloc, int hh, int dir) {
;     ...
;                     u32x2 pk; pk.x = raw[od][2 * hc]; pk.y = raw[od][2 * hc + 1];
;                     if (sec == 0) pv[od & 3] = pk;
;                     else if (sec == 1) { *(LAS u32x2*)(BN + (i0 + od) * LDS_ + c8 + 4 * hc) = pk; const float wr = __expf(tot - ACUM[i0 + od]) * DT[i0 + od];
;                         u32x2 pw; pw.x = pk2(bflo(pk.x) * wr, bfhi(pk.x) * wr); pw.y = pk2(bflo(pk.y) * wr, bfhi(pk.y) * wr); pv[od & 3] = pw; }
.LBB0_617:
	s_andn2_saveexec_b64 s[50:51], s[50:51]
	s_cbranch_execz .LBB0_619
	v_add_u32_e32 v32, v75, v92
	s_waitcnt vmcnt(9)
	ds_write_b64 v32, v[10:11] offset:35992
	v_and_b32_e32 v34, 0xffff0000, v10
	v_mov_b32_e32 v32, v158
	v_lshlrev_b32_e32 v33, 16, v10
	v_mul_f32_e32 v33, v32, v33
	v_mul_f32_e32 v34, v32, v34
	v_cvt_pk_bf16_f32 v138, v33, v34
	v_lshlrev_b32_e32 v33, 16, v11
	v_and_b32_e32 v34, 0xffff0000, v11
	v_mul_f32_e32 v33, v32, v33
	v_mul_f32_e32 v32, v32, v34
	v_cvt_pk_bf16_f32 v142, v33, v32

; #define LAS __attribute__((address_space(3)))
; __device__ __forceinline__ unsigned pk2(float lo, float hi) { return pg8::cvt_pk_bf16(lo, hi); }
; __device__ __forceinline__ void ssd_item(LAS unsigned char* lds, const bf16* proj, const bf16* cxb, bf16* yout, const float* dt_bias, const float* a_log, const float* dskip,
;                                          int gv, int vloc, int hh, int dir) {
;     ...
;                     u32x2 pk; pk.x = raw[od][2 * hc]; pk.y = raw[od][2 * hc + 1];
;                     if (sec == 0) pv[od & 3] = pk;
;                     else if (sec == 1) { *(LAS u32x2*)(BN + (i0 + od) * LDS_ + c8 + 4 * hc) = pk; const float wr = __expf(tot - ACUM[i0 + od]) * DT[i0 + od];
;                         u32x2 pw; pw.x = pk2(bflo(pk.x) * wr, bfhi(pk.x) * wr); pw.y = pk2(bflo(pk.y) * wr, bfhi(pk.y) * wr); pv[od & 3] = pw; }
.LBB0_623:
	s_andn2_saveexec_b64 s[50:51], s[50:51]
	s_cbranch_execz .LBB0_625
	v_add_u32_e32 v32, v75, v92
	s_waitcnt vmcnt(8)
	ds_write_b64 v32, v[14:15] offset:36136
	v_and_b32_e32 v34, 0xffff0000, v14
	v_mov_b32_e32 v32, v159
	v_lshlrev_b32_e32 v33, 16, v14
	v_mul_f32_e32 v33, v32, v33
	v_mul_f32_e32 v34, v32, v34
	v_cvt_pk_bf16_f32 v139, v33, v34
	v_lshlrev_b32_e32 v33, 16, v15
	v_and_b32_e32 v34, 0xffff0000, v15
	v_mul_f32_e32 v33, v32, v33
	v_mul_f32_e32 v32, v32, v34
	v_cvt_pk_bf16_f32 v143, v33, v32

; #define LAS __attribute__((address_space(3)))
; __device__ __forceinline__ unsigned pk2(float lo, float hi) { return pg8::cvt_pk_bf16(lo, hi); }
; __device__ __forceinline__ void ssd_item(LAS unsigned char* lds, const bf16* proj, const bf16* cxb, bf16* yout, const float* dt_bias, const float* a_log, const float* dskip,
;                                          int gv, int vloc, int hh, int dir) {
;     ...
;                     u32x2 pk; pk.x = raw[od][2 * hc]; pk.y = raw[od][2 * hc + 1];
;                     if (sec == 0) pv[od & 3] = pk;
;                     else if (sec == 1) { *(LAS u32x2*)(BN + (i0 + od) * LDS_ + c8 + 4 * hc) = pk; const float wr = __expf(tot - ACUM[i0 + od]) * DT[i0 + od];
;                         u32x2 pw; pw.x = pk2(bflo(pk.x) * wr, bfhi(pk.x) * wr); pw.y = pk2(bflo(pk.y) * wr, bfhi(pk.y) * wr); pv[od & 3] = pw; }
.LBB0_630:
	s_andn2_saveexec_b64 s[50:51], s[50:51]
	s_cbranch_execz .LBB0_632
	v_add_u32_e32 v32, v75, v92
	s_waitcnt vmcnt(7)
	ds_write_b64 v32, v[18:19] offset:36280
	v_and_b32_e32 v34, 0xffff0000, v18
	v_mov_b32_e32 v32, v160
	v_lshlrev_b32_e32 v33, 16, v18
	v_mul_f32_e32 v33, v32, v33
	v_mul_f32_e32 v34, v32, v34
	v_cvt_pk_bf16_f32 v113, v33, v34
	v_lshlrev_b32_e32 v33, 16, v19
	v_and_b32_e32 v34, 0xffff0000, v19
	v_mul_f32_e32 v33, v32, v33
	v_mul_f32_e32 v32, v32, v34
	v_cvt_pk_bf16_f32 v140, v33, v32

; #define LAS __attribute__((address_space(3)))
; __device__ __forceinline__ unsigned pk2(float lo, float hi) { return pg8::cvt_pk_bf16(lo, hi); }
; __device__ __forceinline__ void ssd_item(LAS unsigned char* lds, const bf16* proj, const bf16* cxb, bf16* yout, const float* dt_bias, const float* a_log, const float* dskip,
;                                          int gv, int vloc, int hh, int dir) {
;     ...
;                     u32x2 pk; pk.x = raw[od][2 * hc]; pk.y = raw[od][2 * hc + 1];
;                     if (sec == 0) pv[od & 3] = pk;
;                     else if (sec == 1) { *(LAS u32x2*)(BN + (i0 + od) * LDS_ + c8 + 4 * hc) = pk; const float wr = __expf(tot - ACUM[i0 + od]) * DT[i0 + od];
;                         u32x2 pw; pw.x = pk2(bflo(pk.x) * wr, bfhi(pk.x) * wr); pw.y = pk2(bflo(pk.y) * wr, bfhi(pk.y) * wr); pv[od & 3] = pw; }
.LBB0_636:
	s_andn2_saveexec_b64 s[50:51], s[50:51]
	s_cbranch_execz .LBB0_638
	v_add_u32_e32 v32, v75, v92
	s_waitcnt vmcnt(6)
	ds_write_b64 v32, v[22:23] offset:36424
	v_and_b32_e32 v34, 0xffff0000, v22
	v_mov_b32_e32 v32, v161
	v_lshlrev_b32_e32 v33, 16, v22
	v_mul_f32_e32 v33, v32, v33
	v_mul_f32_e32 v34, v32, v34
	v_cvt_pk_bf16_f32 v137, v33, v34
	v_lshlrev_b32_e32 v33, 16, v23
	v_and_b32_e32 v34, 0xffff0000, v23
	v_mul_f32_e32 v33, v32, v33
	v_mul_f32_e32 v32, v32, v34
	v_cvt_pk_bf16_f32 v141, v33, v32

; #define LAS __attribute__((address_space(3)))
; __device__ __forceinline__ unsigned pk2(float lo, float hi) { return pg8::cvt_pk_bf16(lo, hi); }
; __device__ __forceinline__ void ssd_item(LAS unsigned char* lds, const bf16* proj, const bf16* cxb, bf16* yout, const float* dt_bias, const float* a_log, const float* dskip,
;                                          int gv, int vloc, int hh, int dir) {
;     ...
;                     u32x2 pk; pk.x = raw[od][2 * hc]; pk.y = raw[od][2 * hc + 1];
;                     if (sec == 0) pv[od & 3] = pk;
;                     else if (sec == 1) { *(LAS u32x2*)(BN + (i0 + od) * LDS_ + c8 + 4 * hc) = pk; const float wr = __expf(tot - ACUM[i0 + od]) * DT[i0 + od];
;                         u32x2 pw; pw.x = pk2(bflo(pk.x) * wr, bfhi(pk.x) * wr); pw.y = pk2(bflo(pk.y) * wr, bfhi(pk.y) * wr); pv[od & 3] = pw; }
.LBB0_642:
	s_andn2_saveexec_b64 s[50:51], s[50:51]
	s_cbranch_execz .LBB0_644
	v_add_u32_e32 v32, v75, v92
	s_waitcnt vmcnt(5)
	ds_write_b64 v32, v[26:27] offset:36568
	v_and_b32_e32 v34, 0xffff0000, v26
	v_mov_b32_e32 v32, v162
	v_lshlrev_b32_e32 v33, 16, v26
	v_mul_f32_e32 v33, v32, v33
	v_mul_f32_e32 v34, v32, v34
	v_cvt_pk_bf16_f32 v138, v33, v34
	v_lshlrev_b32_e32 v33, 16, v27
	v_and_b32_e32 v34, 0xffff0000, v27
	v_mul_f32_e32 v33, v32, v33
	v_mul_f32_e32 v32, v32, v34
	v_cvt_pk_bf16_f32 v142, v33, v32

; #define LAS __attribute__((address_space(3)))
; __device__ __forceinline__ unsigned pk2(float lo, float hi) { return pg8::cvt_pk_bf16(lo, hi); }
; __device__ __forceinline__ void ssd_item(LAS unsigned char* lds, const bf16* proj, const bf16* cxb, bf16* yout, const float* dt_bias, const float* a_log, const float* dskip,
;                                          int gv, int vloc, int hh, int dir) {
;     ...
;                     u32x2 pk; pk.x = raw[od][2 * hc]; pk.y = raw[od][2 * hc + 1];
;                     if (sec == 0) pv[od & 3] = pk;
;                     else if (sec == 1) { *(LAS u32x2*)(BN + (i0 + od) * LDS_ + c8 + 4 * hc) = pk; const float wr = __expf(tot - ACUM[i0 + od]) * DT[i0 + od];
;                         u32x2 pw; pw.x = pk2(bflo(pk.x) * wr, bfhi(pk.x) * wr); pw.y = pk2(bflo(pk.y) * wr, bfhi(pk.y) * wr); pv[od & 3] = pw; }
.LBB0_648:
	s_andn2_saveexec_b64 s[50:51], s[50:51]
	s_cbranch_execz .LBB0_650
	v_add_u32_e32 v32, v75, v92
	s_waitcnt vmcnt(4)
	ds_write_b64 v32, v[30:31] offset:36712
	v_and_b32_e32 v34, 0xffff0000, v30
	v_mov_b32_e32 v32, v163
	v_lshlrev_b32_e32 v33, 16, v30
	v_mul_f32_e32 v33, v32, v33
	v_mul_f32_e32 v34, v32, v34
	v_cvt_pk_bf16_f32 v139, v33, v34
	v_lshlrev_b32_e32 v33, 16, v31
	v_and_b32_e32 v34, 0xffff0000, v31
	v_mul_f32_e32 v33, v32, v33
	v_mul_f32_e32 v32, v32, v34
	v_cvt_pk_bf16_f32 v143, v33, v32
